# P8: 3 pm-groups of workgroups staggered 0/9/18us (critical 3-tile WGs undelayed)
# speedup vs baseline: 1.0055x; 1.0027x over previous
.LBB0_1115:
	v_readlane_b32 s0, v246, 4
	v_readlane_b32 s1, v246, 5
	s_cmp_lt_i32 s0, 9
	s_cselect_b64 s[0:1], -1, 0
	s_and_b64 s[2:3], s[0:1], s[2:3]
	s_andn2_b64 vcc, exec, s[2:3]
	s_cbranch_vccnz .LBB0_1150
	s_bfe_u32 s8, s30, 0x30003
	s_cmp_lt_u32 s8, 3
	s_cbranch_scc1 .Lstg8_done
	s_sleep 127
	s_sleep 127
	s_sleep 40
	s_cmp_lt_u32 s8, 6
	s_cbranch_scc1 .Lstg8_done
	s_sleep 127
	s_sleep 127
	s_sleep 40
